# v009 + rope/transposes XCD-local with local barrier after W_in GEMM (isolating this change)
# baseline (speedup 1.0000x reference)
; #define INP(i) ldsptr(lds, (i))
; __global__ void __launch_bounds__(512, 2) mega_fwd(Args a) {
;     ...
;                 const gfloat* qn_p = INP(I_QN); const gfloat* kn_p = INP(I_KN);
;                 for (int wi = gw; wi < CH * 2 / 8; wi += 2 * NGW) {
;                     const int sub = lane & 7;
;                     gbf16* pp[2]; u32x4 vv[2]; int posv[2], hhv[2];
; #pragma unroll
;                     for (int q = 0; q < 2; ++q) { const int item = (wi + q * NGW) * 8 + (lane >> 3); const int tok = item / 2, hh = 8 + (item & 1);
;                         pp[q] = proj + (size_t)tok * PROJ + 64 * hh + 8 * sub; vv[q] = *(const gu32x4*)pp[q]; posv[q] = tok % S_; hhv[q] = hh; }
; #pragma unroll
;                     for (int q = 0; q < 2; ++q) {
;                         const u32x4 v = vv[q]; const int hh = hhv[q], pos = posv[q];
;                         float x[8] = {bflo(v.x), bfhi(v.x), bflo(v.y), bfhi(v.y), bflo(v.z), bfhi(v.z), bflo(v.w), bfhi(v.w)};
;                         float ss = 0.f;
; #pragma unroll
;                         for (int e = 0; e < 8; ++e) ss += x[e] * x[e];
;                         ss += __shfl_xor(ss, 1); ss += __shfl_xor(ss, 2); ss += __shfl_xor(ss, 4);
;                         const float rstd = (1.0f / sqrtf(ss * (1.0f / 64) + EPS)) * ((hh < 8) ? 0.125f * LOG2E : 1.0f);
;                         const gfloat* gn = ((hh < 8) ? qn_p : kn_p) + 8 * sub;
;                         const f32x4 g0 = *(const gf32x4*)gn, g1 = *(const gf32x4*)(gn + 4);
;                         x[0] *= rstd * g0.x; x[1] *= rstd * g0.y; x[2] *= rstd * g0.z; x[3] *= rstd * g0.w;
;                         x[4] *= rstd * g1.x; x[5] *= rstd * g1.y; x[6] *= rstd * g1.z; x[7] *= rstd * g1.w;
;                         const int nidx = (sub < 4) ? (pos >> 6) : (pos & 63);
;                         const gf32x4* rt = (const gf32x4*)(rope + nidx * 16 + 4 * (sub & 3));
;                         const f32x4 c01 = rt[0], c23 = rt[1];
;                         float y[8];
;                         y[0] = x[0] * c01.x - x[1] * c01.y; y[1] = x[0] * c01.y + x[1] * c01.x;
;                         y[2] = x[2] * c01.z - x[3] * c01.w; y[3] = x[2] * c01.w + x[3] * c01.z;
;                         y[4] = x[4] * c23.x - x[5] * c23.y; y[5] = x[4] * c23.y + x[5] * c23.x;
;                         y[6] = x[6] * c23.z - x[7] * c23.w; y[7] = x[6] * c23.w + x[7] * c23.z;
.LBB0_540:
	v_readlane_b32 s6, v255, 6
	s_ashr_i32 s41, s6, 6
	v_readlane_b32 s0, v254, 42
	s_add_i32 s10, s0, s41
	s_add_u32 s70, s84, 0x3c40a000
	s_addc_u32 s71, s85, 0
	s_and_b32 s11, 0xffff, s40
	s_movk_i32 s47, 0x100
	v_and_b32_e32 v208, 63, v240
	s_cmp_lt_i32 s11, 3
	s_mov_b64 s[0:1], -1
	s_cbranch_scc1 .LBB0_573
	s_cmp_gt_i32 s11, 3
	s_cbranch_scc0 .LBB0_549
	v_readlane_b32 s0, v254, 62
	s_cmpk_gt_i32 s10, 0x1fff
	v_lshrrev_b32_e32 v6, 3, v208
	v_mov_b32_e32 v0, s0
	s_waitcnt lgkmcnt(0)
	ds_read_b64 v[2:3], v0
	s_waitcnt lgkmcnt(0)
	v_readfirstlane_b32 s1, v3
	v_readfirstlane_b32 s0, v2
	s_cbranch_scc1 .LBB0_545
	v_cvt_f32_u32_e32 v5, s38
	v_lshlrev_b32_e32 v0, 4, v208
	v_and_b32_e32 v4, 7, v240
	v_and_b32_e32 v0, 0x80, v0
	v_lshl_add_u64 v[2:3], s[96:97], 0, v[0:1]
	v_lshlrev_b32_e32 v0, 4, v4
	v_lshl_add_u64 v[8:9], v[2:3], 0, v[0:1]
	v_rcp_iflag_f32_e32 v2, v5
	v_lshlrev_b32_e32 v0, 5, v240
	v_and_b32_e32 v0, 0x60, v0
	v_lshl_add_u64 v[10:11], s[66:67], 0, v[0:1]
	v_mul_f32_e32 v0, 0x4f7ffffe, v2
	v_cvt_u32_f32_e32 v2, v0
	v_lshlrev_b32_e32 v0, 5, v4
	v_lshl_add_u64 v[12:13], s[0:1], 0, v[0:1]
	s_sub_i32 s0, 0, s38
	v_mul_lo_u32 v0, s0, v2
	s_lshl_b32 s0, s41, 3
	v_readlane_b32 s1, v254, 50
	v_mul_hi_u32 v0, v2, v0
	s_add_i32 s0, s1, s0
	v_readlane_b32 s1, v254, 51
	v_cmp_gt_u32_e64 s[2:3], 4, v4
	v_add_u32_e32 v0, v2, v0
	v_add_u32_e32 v7, s1, v6
	s_mov_b32 s1, s10
	s_mov_b32 s43, s12
	s_mov_b32 s44, s19
	s_movk_i32 s45, 0x1fff
	s_and_b64 vcc, exec, s[90:91]
	s_cbranch_vccz .Lk4_nolocal_a
	v_readlane_b32 s43, v255, 7
	v_readlane_b32 s44, v255, 8
	s_lshl_b32 s0, s43, 13
	s_lshl_b32 s44, s44, 3
	s_add_i32 s0, s0, s44
	s_lshl_b32 s44, s41, 3
	s_add_i32 s0, s0, s44
	v_add_u32_e32 v7, 0x800, v6
	s_mov_b32 s1, 0
	s_movk_i32 s43, 0x200
	s_movk_i32 s44, 0x1000
	s_movk_i32 s45, 0x3ff
.Lk4_nolocal_a:
.LBB0_544:
	s_nop 0
	v_add_u32_e32 v2, s0, v6
	v_lshrrev_b32_e32 v3, 31, v2
	v_add_u32_e32 v2, v2, v3
	v_ashrrev_i32_e32 v3, 1, v2
	v_mad_i64_i32 v[14:15], s[4:5], v3, s33, v[8:9]
	global_load_dwordx4 v[18:21], v[14:15], off offset:1024
	v_sub_u32_e32 v4, 0, v3
	v_max_i32_e32 v3, v3, v4
	v_mul_hi_u32 v4, v3, v0
	v_mul_lo_u32 v4, v4, s38
	v_sub_u32_e32 v3, v3, v4
	v_cmp_le_u32_e32 vcc, s38, v3
	v_subrev_u32_e32 v4, s38, v3
	v_ashrrev_i32_e32 v2, 31, v2
	v_cndmask_b32_e32 v3, v3, v4, vcc
	v_cmp_le_u32_e32 vcc, s38, v3
	v_subrev_u32_e32 v4, s38, v3
	s_add_i32 s1, s1, s43
	v_cndmask_b32_e32 v3, v3, v4, vcc
	v_xor_b32_e32 v3, v3, v2
	v_sub_u32_e32 v29, v3, v2
	v_add_u32_e32 v2, s0, v7
	v_lshrrev_b32_e32 v3, 31, v2
	v_add_u32_e32 v22, v2, v3
	v_ashrrev_i32_e32 v23, 1, v22
	v_sub_u32_e32 v24, 0, v23
	v_mad_i64_i32 v[16:17], s[4:5], v23, s33, v[8:9]
	v_max_i32_e32 v23, v23, v24
	v_mul_hi_u32 v24, v23, v0
	v_mul_lo_u32 v24, v24, s38
	v_sub_u32_e32 v23, v23, v24
	v_cmp_le_u32_e32 vcc, s38, v23
	v_subrev_u32_e32 v24, s38, v23
	v_ashrrev_i32_e32 v22, 31, v22
	v_cndmask_b32_e32 v23, v23, v24, vcc
	v_cmp_le_u32_e32 vcc, s38, v23
	v_subrev_u32_e32 v24, s38, v23
	global_load_dwordx4 v[2:5], v[16:17], off offset:1024
	v_cndmask_b32_e32 v23, v23, v24, vcc
	v_xor_b32_e32 v23, v23, v22
	v_sub_u32_e32 v35, v23, v22
	s_add_i32 s0, s0, s44
	s_cmp_gt_i32 s1, s45
	s_waitcnt vmcnt(0)
	v_and_b32_e32 v30, 0xffff0000, v18
	v_lshlrev_b32_e32 v28, 16, v18
	v_mul_f32_e32 v22, v30, v30
	v_lshlrev_b32_e32 v31, 16, v19
	v_fmac_f32_e32 v22, v28, v28
	v_and_b32_e32 v32, 0xffff0000, v19
	v_fmac_f32_e32 v22, v31, v31
	v_lshlrev_b32_e32 v33, 16, v20
	v_fmac_f32_e32 v22, v32, v32
	v_and_b32_e32 v36, 0xffff0000, v20
	v_fmac_f32_e32 v22, v33, v33
	v_lshlrev_b32_e32 v18, 16, v21
	v_and_b32_e32 v19, 0xffff0000, v21
	v_fmac_f32_e32 v22, v36, v36
	v_pk_mul_f32 v[20:21], v[18:19], v[18:19]
	s_nop 0
	v_add_f32_e32 v20, v22, v20
	v_add_f32_e32 v20, v20, v21
	ds_bpermute_b32 v21, v231, v20
	s_waitcnt lgkmcnt(0)
	v_add_f32_e32 v20, v20, v21
	ds_bpermute_b32 v21, v232, v20
	s_waitcnt lgkmcnt(0)
	v_add_f32_e32 v20, v20, v21
	ds_bpermute_b32 v21, v233, v20
	s_waitcnt lgkmcnt(0)
	v_add_f32_e32 v20, v20, v21
	v_fmamk_f32 v20, v20, 0x3c800000, v235
	v_cmp_gt_f32_e32 vcc, s22, v20
	v_mul_f32_e32 v21, 0x4f800000, v20
	s_nop 0
	v_cndmask_b32_e32 v20, v20, v21, vcc
	v_sqrt_f32_e32 v21, v20
	s_nop 0
	v_add_u32_e32 v22, -1, v21
	v_fma_f32 v23, -v22, v21, v20
	v_cmp_ge_f32_e64 s[4:5], 0, v23
	v_add_u32_e32 v23, 1, v21
	s_nop 0
	v_cndmask_b32_e64 v22, v21, v22, s[4:5]
	v_fma_f32 v21, -v23, v21, v20
	v_cmp_lt_f32_e64 s[4:5], 0, v21
	s_nop 1
	v_cndmask_b32_e64 v21, v22, v23, s[4:5]
	v_mul_f32_e32 v22, 0x37800000, v21
	v_cndmask_b32_e32 v21, v21, v22, vcc
	v_cmp_class_f32_e32 vcc, v20, v238
	s_nop 1
	v_cndmask_b32_e32 v20, v21, v20, vcc
	v_div_scale_f32 v21, s[4:5], v20, v20, 1.0
	v_rcp_f32_e32 v22, v21
	s_nop 0
	v_fma_f32 v23, -v21, v22, 1.0
	v_fmac_f32_e32 v22, v23, v22
	v_div_scale_f32 v23, vcc, 1.0, v20, 1.0
	v_mul_f32_e32 v24, v23, v22
	v_fma_f32 v25, -v21, v24, v23
	v_fmac_f32_e32 v24, v25, v22
	v_fma_f32 v21, -v21, v24, v23
	v_div_fmas_f32 v21, v21, v22, v24
	v_div_fixup_f32 v37, v21, v20, 1.0
	global_load_dwordx4 v[20:23], v[12:13], off offset:16
	global_load_dwordx4 v[24:27], v[12:13], off
	s_waitcnt vmcnt(1)
	v_mul_f32_e32 v20, v20, v37
	v_mul_f32_e32 v34, v20, v33
	v_mul_f32_e32 v20, v21, v37
	v_mul_f32_e32 v36, v20, v36
	v_mul_f32_e32 v20, v22, v37
	v_mul_f32_e32 v38, v20, v18
	v_mul_f32_e32 v18, v23, v37
	v_mul_f32_e32 v40, v18, v19
	v_ashrrev_i32_e32 v18, 6, v29
	v_and_b32_e32 v19, 63, v29
	s_waitcnt vmcnt(0)
; __device__ __forceinline__ unsigned pk2(float lo, float hi) { f32x2 v = {lo, hi}; bf16x2_t b = __builtin_convertvector(v, bf16x2_t); return __builtin_bit_cast(unsigned, b); }
; __device__ __forceinline__ float bflo(unsigned w) { return __uint_as_float(w << 16); }
; __device__ __forceinline__ float bfhi(unsigned w) { return __uint_as_float(w & 0xffff0000u); }
; __global__ void __launch_bounds__(512, 2) mega_fwd(Args a) {
;     ...
;                     for (int q = 0; q < 2; ++q) {
;                         const u32x4 v = vv[q]; const int hh = hhv[q], pos = posv[q];
;                         float x[8] = {bflo(v.x), bfhi(v.x), bflo(v.y), bfhi(v.y), bflo(v.z), bfhi(v.z), bflo(v.w), bfhi(v.w)};
;                         float ss = 0.f;
; #pragma unroll
;                         for (int e = 0; e < 8; ++e) ss += x[e] * x[e];
;                         ss += __shfl_xor(ss, 1); ss += __shfl_xor(ss, 2); ss += __shfl_xor(ss, 4);
;                         const float rstd = (1.0f / sqrtf(ss * (1.0f / 64) + EPS)) * ((hh < 8) ? 0.125f * LOG2E : 1.0f);
;                         const gfloat* gn = ((hh < 8) ? qn_p : kn_p) + 8 * sub;
;                         const f32x4 g0 = *(const gf32x4*)gn, g1 = *(const gf32x4*)(gn + 4);
;                         x[0] *= rstd * g0.x; x[1] *= rstd * g0.y; x[2] *= rstd * g0.z; x[3] *= rstd * g0.w;
;                         x[4] *= rstd * g1.x; x[5] *= rstd * g1.y; x[6] *= rstd * g1.z; x[7] *= rstd * g1.w;
;                         const int nidx = (sub < 4) ? (pos >> 6) : (pos & 63);
;                         const gf32x4* rt = (const gf32x4*)(rope + nidx * 16 + 4 * (sub & 3));
;                         const f32x4 c01 = rt[0], c23 = rt[1];
;                         float y[8];
;                         y[0] = x[0] * c01.x - x[1] * c01.y; y[1] = x[0] * c01.y + x[1] * c01.x;
;                         y[2] = x[2] * c01.z - x[3] * c01.w; y[3] = x[2] * c01.w + x[3] * c01.z;
;                         y[4] = x[4] * c23.x - x[5] * c23.y; y[5] = x[4] * c23.y + x[5] * c23.x;
;                         y[6] = x[6] * c23.z - x[7] * c23.w; y[7] = x[6] * c23.w + x[7] * c23.z;
;                         u32x4 w; w.x = pk2(y[0], y[1]); w.y = pk2(y[2], y[3]); w.z = pk2(y[4], y[5]); w.w = pk2(y[6], y[7]);
;                         *(gu32x4*)pp[q] = w;
;                     }
	v_mul_f32_e32 v24, v24, v37
	v_cndmask_b32_e64 v18, v19, v18, s[2:3]
	v_mul_f32_e32 v28, v24, v28
	v_mul_f32_e32 v24, v25, v37
	v_lshlrev_b32_e32 v18, 4, v18
	v_mul_f32_e32 v30, v24, v30
	v_mul_f32_e32 v24, v26, v37
	v_ashrrev_i32_e32 v19, 31, v18
	v_mul_f32_e32 v26, v24, v31
	v_mul_f32_e32 v24, v27, v37
	v_lshl_add_u64 v[22:23], v[18:19], 3, v[10:11]
	v_mul_f32_e32 v32, v24, v32
	global_load_dwordx4 v[18:21], v[22:23], off offset:16
	s_nop 0
	global_load_dwordx4 v[22:25], v[22:23], off
	s_waitcnt vmcnt(0)
	v_pk_mul_f32 v[30:31], v[22:23], v[30:31] op_sel:[1,0] op_sel_hi:[0,0]
	v_pk_fma_f32 v[42:43], v[22:23], v[28:29], v[30:31] neg_lo:[0,0,1] neg_hi:[0,0,1]
	v_pk_fma_f32 v[22:23], v[22:23], v[28:29], v[30:31] op_sel_hi:[1,0,1]
	v_pk_mul_f32 v[28:29], v[24:25], v[32:33] op_sel:[1,0] op_sel_hi:[0,0]
	v_pk_fma_f32 v[30:31], v[24:25], v[26:27], v[28:29] neg_lo:[0,0,1] neg_hi:[0,0,1]
	v_pk_fma_f32 v[24:25], v[24:25], v[26:27], v[28:29] op_sel_hi:[1,0,1]
	v_pk_mul_f32 v[26:27], v[18:19], v[36:37] op_sel:[1,0] op_sel_hi:[0,0]
	v_pk_fma_f32 v[28:29], v[18:19], v[34:35], v[26:27] neg_lo:[0,0,1] neg_hi:[0,0,1]
	v_pk_fma_f32 v[26:27], v[18:19], v[34:35], v[26:27] op_sel_hi:[1,0,1]
	v_pk_mul_f32 v[18:19], v[20:21], v[40:41] op_sel:[1,0] op_sel_hi:[0,0]
	v_pk_fma_f32 v[32:33], v[20:21], v[38:39], v[18:19] neg_lo:[0,0,1] neg_hi:[0,0,1]
	v_pk_fma_f32 v[20:21], v[20:21], v[38:39], v[18:19] op_sel_hi:[1,0,1]
	v_cvt_pk_bf16_f32 v18, v42, v23
	v_and_b32_e32 v23, 0xffff0000, v2
	v_lshlrev_b32_e32 v22, 16, v2
	v_lshlrev_b32_e32 v29, 16, v4
	v_and_b32_e32 v31, 0xffff0000, v4
	v_mul_f32_e32 v4, v23, v23
	v_cvt_pk_bf16_f32 v19, v30, v25
	v_lshlrev_b32_e32 v25, 16, v3
	v_fmac_f32_e32 v4, v22, v22
	v_cvt_pk_bf16_f32 v20, v28, v27
	v_and_b32_e32 v27, 0xffff0000, v3
	v_fmac_f32_e32 v4, v25, v25
	v_cvt_pk_bf16_f32 v21, v32, v21
	v_fmac_f32_e32 v4, v27, v27
	global_store_dwordx4 v[14:15], v[18:21], off offset:1024
	v_fmac_f32_e32 v4, v29, v29
	v_lshlrev_b32_e32 v14, 16, v5
	v_and_b32_e32 v15, 0xffff0000, v5
	v_fmac_f32_e32 v4, v31, v31
	v_pk_mul_f32 v[2:3], v[14:15], v[14:15]
	s_nop 0
	v_add_f32_e32 v2, v4, v2
	v_add_f32_e32 v2, v2, v3
	ds_bpermute_b32 v3, v231, v2
	s_waitcnt lgkmcnt(0)
	v_add_f32_e32 v2, v2, v3
	ds_bpermute_b32 v3, v232, v2
	s_waitcnt lgkmcnt(0)
	v_add_f32_e32 v2, v2, v3
	ds_bpermute_b32 v3, v233, v2
	s_waitcnt lgkmcnt(0)
	v_add_f32_e32 v2, v2, v3
	v_fmamk_f32 v2, v2, 0x3c800000, v235
	v_cmp_gt_f32_e32 vcc, s22, v2
	v_mul_f32_e32 v3, 0x4f800000, v2
	s_nop 0
	v_cndmask_b32_e32 v2, v2, v3, vcc
	v_sqrt_f32_e32 v3, v2
	s_nop 0
	v_add_u32_e32 v4, -1, v3
	v_fma_f32 v5, -v4, v3, v2
	v_cmp_ge_f32_e64 s[4:5], 0, v5
	v_add_u32_e32 v5, 1, v3
	s_nop 0
	v_cndmask_b32_e64 v4, v3, v4, s[4:5]
	v_fma_f32 v3, -v5, v3, v2
	v_cmp_lt_f32_e64 s[4:5], 0, v3
	s_nop 1
	v_cndmask_b32_e64 v3, v4, v5, s[4:5]
	v_mul_f32_e32 v4, 0x37800000, v3
	v_cndmask_b32_e32 v3, v3, v4, vcc
	v_cmp_class_f32_e32 vcc, v2, v238
	s_nop 1
	v_cndmask_b32_e32 v2, v3, v2, vcc
	v_div_scale_f32 v3, s[4:5], v2, v2, 1.0
	v_rcp_f32_e32 v4, v3
	s_nop 0
	v_fma_f32 v5, -v3, v4, 1.0
	v_fmac_f32_e32 v4, v5, v4
	v_div_scale_f32 v5, vcc, 1.0, v2, 1.0
	v_mul_f32_e32 v18, v5, v4
	v_fma_f32 v19, -v3, v18, v5
	v_fmac_f32_e32 v18, v19, v4
	v_fma_f32 v3, -v3, v18, v5
	v_div_fmas_f32 v3, v3, v4, v18
	v_div_fixup_f32 v33, v3, v2, 1.0
	global_load_dwordx4 v[2:5], v[12:13], off offset:16
	global_load_dwordx4 v[18:21], v[12:13], off
	s_waitcnt vmcnt(1)
	v_mul_f32_e32 v2, v2, v33
	v_mul_f32_e32 v30, v2, v29
	v_mul_f32_e32 v2, v3, v33
	v_mul_f32_e32 v32, v2, v31
	v_mul_f32_e32 v2, v4, v33
	v_mul_f32_e32 v14, v2, v14
	v_mul_f32_e32 v2, v5, v33
	s_waitcnt vmcnt(0)
	v_mul_f32_e32 v18, v18, v33
	v_mul_f32_e32 v34, v2, v15
	v_ashrrev_i32_e32 v2, 6, v35
	v_and_b32_e32 v3, 63, v35
	v_mul_f32_e32 v22, v18, v22
	v_mul_f32_e32 v18, v19, v33
	v_cndmask_b32_e64 v2, v3, v2, s[2:3]
	v_mul_f32_e32 v24, v18, v23
	v_mul_f32_e32 v18, v20, v33
	v_lshlrev_b32_e32 v2, 4, v2
	v_mul_f32_e32 v26, v18, v25
	v_mul_f32_e32 v18, v21, v33
	v_ashrrev_i32_e32 v3, 31, v2
	v_mul_f32_e32 v28, v18, v27
	v_lshl_add_u64 v[18:19], v[2:3], 3, v[10:11]
	global_load_dwordx4 v[2:5], v[18:19], off offset:16
	s_nop 0
	global_load_dwordx4 v[18:21], v[18:19], off
	s_waitcnt vmcnt(0)
	v_pk_mul_f32 v[24:25], v[18:19], v[24:25] op_sel:[1,0] op_sel_hi:[0,0]
	v_pk_fma_f32 v[36:37], v[18:19], v[22:23], v[24:25] neg_lo:[0,0,1] neg_hi:[0,0,1]
	v_pk_fma_f32 v[18:19], v[18:19], v[22:23], v[24:25] op_sel_hi:[1,0,1]
	v_pk_mul_f32 v[22:23], v[20:21], v[28:29] op_sel:[1,0] op_sel_hi:[0,0]
	v_pk_fma_f32 v[24:25], v[20:21], v[26:27], v[22:23] neg_lo:[0,0,1] neg_hi:[0,0,1]
	v_pk_fma_f32 v[20:21], v[20:21], v[26:27], v[22:23] op_sel_hi:[1,0,1]
	v_pk_mul_f32 v[22:23], v[2:3], v[32:33] op_sel:[1,0] op_sel_hi:[0,0]
	v_pk_fma_f32 v[26:27], v[2:3], v[30:31], v[22:23] neg_lo:[0,0,1] neg_hi:[0,0,1]
	v_pk_fma_f32 v[22:23], v[2:3], v[30:31], v[22:23] op_sel_hi:[1,0,1]
	v_pk_mul_f32 v[2:3], v[4:5], v[34:35] op_sel:[1,0] op_sel_hi:[0,0]
	v_pk_fma_f32 v[28:29], v[4:5], v[14:15], v[2:3] neg_lo:[0,0,1] neg_hi:[0,0,1]
	v_pk_fma_f32 v[4:5], v[4:5], v[14:15], v[2:3] op_sel_hi:[1,0,1]
	v_cvt_pk_bf16_f32 v2, v36, v19
	v_cvt_pk_bf16_f32 v3, v24, v21
	v_cvt_pk_bf16_f32 v4, v26, v23
	v_cvt_pk_bf16_f32 v5, v28, v5
	global_store_dwordx4 v[16:17], v[2:5], off offset:1024
	s_cbranch_scc0 .LBB0_544
; #define LAS __attribute__((address_space(3)))
; __global__ void __launch_bounds__(512, 2) mega_fwd(Args a) {
;     ...
;                 LAS unsigned short* scr = (LAS unsigned short*)(lds + wave * 16384);
;                 for (int it = gw; it < (CH / 64) * 4; it += NGW) {
;                     const int kvh = it & 1, which = (it >> 1) & 1, tt = it >> 2;
;                     const int tok = 64 * tt, seq = tok / S_, pos = tok % S_;
;                     transpose64_bf16(proj + (size_t)tok * PROJ + (which ? 1408 : 640) + 64 * kvh, PROJ,
;                                      (which ? vtb : vta) + ((size_t)(seq * 2 + kvh) * 64) * S_ + pos, S_, scr, lane);
;                 }
.LBB0_545:
	s_and_b64 vcc, exec, s[90:91]
	s_cbranch_vccz .Lk4_nolocal_b
	v_readlane_b32 s43, v255, 7
	v_readlane_b32 s44, v255, 8
	s_lshl_b32 s10, s43, 8
	s_add_i32 s10, s10, s44
	s_add_i32 s10, s10, s41
.Lk4_nolocal_b:
	s_cmpk_gt_i32 s10, 0x7ff
	s_cbranch_scc1 .LBB0_548
	s_lshl_b32 s0, s41, 14
	v_lshlrev_b32_e32 v0, 3, v208
	s_add_i32 s3, s0, 0
	v_and_b32_e32 v20, 56, v0
	s_and_b64 s[0:1], s[94:95], exec
	v_mul_u32_u24_e32 v32, 0x84, v20
	v_lshlrev_b32_e32 v33, 1, v6
	s_cselect_b32 s2, 11, 13
	v_lshl_add_u32 v21, v20, 1, s3
	v_or_b32_e32 v0, 8, v6
	v_add3_u32 v36, s3, v32, v33
	s_abs_i32 s3, s38
	v_mul_hi_u32_u24_e32 v5, 0x2800, v0
	v_mul_u32_u24_e32 v4, 0x2800, v0
	v_lshlrev_b64 v[32:33], s2, v[0:1]
	v_cvt_f32_u32_e32 v0, s3
	s_bfe_u32 s4, s6, 0x10006
	s_sub_i32 s1, 0, s3
	v_mov_b32_e32 v7, v1
	v_rcp_iflag_f32_e32 v0, v0
	v_or_b32_e32 v22, 16, v6
	v_mov_b32_e32 v23, v1
	v_or_b32_e32 v24, 24, v6
	v_mul_f32_e32 v0, 0x4f7ffffe, v0
	v_cvt_u32_f32_e32 v0, v0
	v_mov_b32_e32 v25, v1
	v_or_b32_e32 v26, 32, v6
	v_mov_b32_e32 v27, v1
	v_readfirstlane_b32 s6, v0
	s_mul_i32 s1, s1, s6
	v_or_b32_e32 v28, 40, v6
	v_mov_b32_e32 v29, v1
	v_or_b32_e32 v30, 48, v6
	v_mov_b32_e32 v31, v1
	v_or_b32_e32 v34, 56, v6
	s_mul_hi_u32 s1, s6, s1
	v_mul_hi_u32_u24_e32 v3, 0x2800, v6
	v_mul_u32_u24_e32 v2, 0x2800, v6
	v_mul_u32_u24_e32 v35, 0x84, v6
	v_mul_hi_u32_u24_e32 v9, 0x2800, v22
	v_mul_u32_u24_e32 v8, 0x2800, v22
	v_mul_hi_u32_u24_e32 v11, 0x2800, v24
	v_mul_u32_u24_e32 v10, 0x2800, v24
	v_mul_hi_u32_u24_e32 v13, 0x2800, v26
	v_mul_u32_u24_e32 v12, 0x2800, v26
	v_mul_hi_u32_u24_e32 v15, 0x2800, v28
	v_mul_u32_u24_e32 v14, 0x2800, v28
	v_mul_hi_u32_u24_e32 v17, 0x2800, v30
	v_mul_u32_u24_e32 v16, 0x2800, v30
	v_mul_u32_u24_e32 v18, 0x2800, v34
	v_lshlrev_b64 v[6:7], s2, v[6:7]
	v_lshlrev_b64 v[22:23], s2, v[22:23]
	v_lshlrev_b64 v[24:25], s2, v[24:25]
	v_lshlrev_b64 v[26:27], s2, v[26:27]
	v_lshlrev_b64 v[28:29], s2, v[28:29]
	v_lshlrev_b64 v[30:31], s2, v[30:31]
	v_lshlrev_b32_e32 v34, s2, v34
	s_lshl_b32 s0, s4, 6
	s_add_i32 s6, s6, s1
	s_lshl_b32 s1, s41, 4
	v_readlane_b32 s7, v254, 53
	v_mov_b32_e32 v19, v1
	s_ashr_i32 s5, s38, 31
	s_add_i32 s7, s7, s1
	s_and_b64 vcc, exec, s[90:91]
	s_cbranch_vccz .Lk4_nolocal_c
	s_lshl_b32 s7, s43, 12
	s_lshl_b32 s44, s44, 4
	s_add_i32 s7, s7, s44
	s_add_i32 s7, s7, s1
.Lk4_nolocal_c:
	s_lshl_b32 s8, s0, 1
	v_lshlrev_b32_e32 v0, 1, v20
	v_add_u32_e32 v37, v21, v35
	v_lshlrev_b32_e32 v6, 1, v6
	v_lshlrev_b32_e32 v20, 1, v32
	v_lshlrev_b32_e32 v22, 1, v22
	v_lshlrev_b32_e32 v24, 1, v24
	v_lshlrev_b32_e32 v26, 1, v26
	v_lshlrev_b32_e32 v28, 1, v28
	v_lshlrev_b32_e32 v30, 1, v30
	v_lshlrev_b32_e32 v32, 1, v34
	s_mov_b32 s9, s10

; __global__ void __launch_bounds__(512, 2) mega_fwd(Args a) {
;     ...
;         if ((step2 & 1) || !dup_) {
;             if (step + 1 < NS) { const int k_ = step % N_PER;
;                 if (xl_good && PH_DUP == 0 && (k_ <= 2 || k_ >= 6)) xcd_local_barrier(xbar);
;                 else xcd_barrier(xbar); }
.LBB0_655:
	s_add_i32 s27, s27, 0xfffa
	s_and_b32 s0, s27, 0xff
	s_cmpk_lt_u32 s0, 0xfe
	s_cselect_b64 s[0:1], -1, 0
	s_and_b64 s[0:1], s[90:91], s[0:1]
	s_andn2_b64 vcc, exec, s[0:1]
	s_mov_b64 s[0:1], -1
	s_cbranch_vccz .LBB0_709
	s_waitcnt vmcnt(0)
	s_waitcnt vmcnt(0) lgkmcnt(0)
	s_barrier
	s_mov_b64 s[0:1], exec
	v_readlane_b32 s2, v254, 2
	v_readlane_b32 s3, v254, 3
	v_readlane_b32 s26, v254, 4
	v_readlane_b32 s10, v254, 6
	v_readlane_b32 s16, v254, 8
	v_readlane_b32 s20, v254, 10
	v_readlane_b32 s28, v254, 12
	v_readlane_b32 s30, v254, 14
	v_readlane_b32 s34, v254, 16
	v_readlane_b32 s36, v254, 18
	v_readlane_b32 s38, v254, 20
	v_readlane_b32 s40, v254, 22
	v_readlane_b32 s42, v254, 24
	v_readlane_b32 s44, v254, 26
	v_readlane_b32 s46, v254, 28
	v_readlane_b32 s48, v254, 30
	v_readlane_b32 s52, v254, 32
	v_readlane_b32 s54, v254, 34
	v_readlane_b32 s56, v254, 36
	s_and_b64 s[2:3], s[0:1], s[2:3]
	v_readlane_b32 s27, v254, 5
	v_readlane_b32 s11, v254, 7
	v_readlane_b32 s17, v254, 9
	v_readlane_b32 s21, v254, 11
	v_readlane_b32 s29, v254, 13
	v_readlane_b32 s31, v254, 15
	v_readlane_b32 s35, v254, 17
	v_readlane_b32 s37, v254, 19
	v_readlane_b32 s39, v254, 21
	v_readlane_b32 s41, v254, 23
	v_readlane_b32 s43, v254, 25
	v_readlane_b32 s45, v254, 27
	v_readlane_b32 s47, v254, 29
	v_readlane_b32 s49, v254, 31
	v_readlane_b32 s53, v254, 33
	v_readlane_b32 s55, v254, 35
	v_readlane_b32 s57, v254, 37
	v_readlane_b32 s12, v254, 47
	s_mov_b64 exec, s[2:3]
	s_cbranch_execz .LBB0_708
	v_readlane_b32 s3, v255, 0
	s_getreg_b32 s2, hwreg(HW_REG_XCC_ID, 0, 4)
	s_waitcnt vmcnt(0) expcnt(0) lgkmcnt(0)
	v_mov_b32_e32 v0, s3
	ds_read_b32 v3, v0
	v_readlane_b32 s3, v255, 1
	s_and_b32 s8, s2, 15
	s_waitcnt lgkmcnt(0)
	v_cmp_ne_u32_e32 vcc, 0, v3
	v_mov_b32_e32 v0, s3
	ds_read_b32 v2, v0
	s_cbranch_vccnz .LBB0_672
	s_mov_b32 s9, 1
	s_branch .LBB0_660
